# P8 chunk images staged by direct global->LDS loads (global_load_lds_dwordx4 into 3 rotating padded images, two steps ahead) instead of VGPR staging + ds_write
# baseline (speedup 1.0000x reference)
.LBB0_906:
	s_cmp_lt_i32 s90, 9
	s_cselect_b64 s[2:3], -1, 0
	s_and_b64 s[38:39], s[2:3], s[0:1]
	s_andn2_b64 vcc, exec, s[38:39]
	s_cbranch_vccnz .LBB0_998
	s_mov_b64 s[70:71], s[62:63]
	s_mov_b32 s68, s59
	s_mov_b64 s[66:67], s[60:61]
	s_cmpk_gt_i32 s58, 0xff
	v_readfirstlane_b32 s20, v0
	s_cbranch_scc1 .LBB0_997
	v_readlane_b32 s15, v251, 48
	v_readfirstlane_b32 s35, v0
	s_lshr_b32 s35, s35, 6
	s_and_b32 s36, s35, 3
	s_lshr_b32 s37, s35, 2
	s_lshl_b32 s95, s35, 10
	s_and_b32 s31, s15, 1
	s_bfe_u32 s73, s15, 0x20001
	s_bfe_u32 s74, s15, 0x20003
	s_lshr_b32 s72, s15, 5
	s_lshl_b32 s33, s72, 8
	s_addk_i32 s33, 0x4000
	s_lshl_b32 s34, s72, 11
	s_addk_i32 s34, 0xff00
	s_movk_i32 s48, 0x1800
	s_movk_i32 s49, 0x400
	s_cmp_eq_u32 s31, 0
	s_cselect_b32 s30, s48, s49
	s_lshl_b32 s48, s73, 8
	s_add_u32 s49, s88, 0xa27d000
	s_addc_u32 s52, s89, 0
	s_cmp_eq_u32 s31, 0
	s_cselect_b32 s16, s96, s49
	s_cselect_b32 s17, s97, s52
	s_add_u32 s16, s16, s48
	s_addc_u32 s17, s17, 0
	s_add_u32 s49, s88, 0xb27d000
	s_addc_u32 s52, s89, 0
	s_add_u32 s53, s96, 0x400
	s_addc_u32 s64, s97, 0
	s_cmp_eq_u32 s31, 0
	s_cselect_b32 s18, s53, s49
	s_cselect_b32 s19, s64, s52
	s_add_u32 s18, s18, s48
	s_addc_u32 s19, s19, 0
	s_lshl_b32 s49, s73, 9
	s_lshl_b32 s52, s74, 7
	s_add_i32 s49, s49, s52
	s_add_i32 s52, s49, 0x800
	s_add_u32 s20, s96, s52
	s_addc_u32 s21, s97, 0
	v_readlane_b32 s28, v251, 34
	v_readlane_b32 s29, v251, 35
	s_lshl_b32 s52, s31, 25
	s_add_i32 s52, s52, s49
	s_add_u32 s28, s28, s52
	s_addc_u32 s29, s29, 0
	s_lshl_b32 s49, s31, 3
	s_add_i32 s49, s49, s72
	s_lshl_b32 s49, s49, 2
	s_add_i32 s49, s49, s73
	s_mul_i32 s49, s49, 0x4800
	s_add_u32 s22, s88, 0x115d000
	s_addc_u32 s23, s89, 0
	s_add_u32 s22, s22, s49
	s_addc_u32 s23, s23, 0
	v_bfe_u32 v94, v0, 4, 2
	v_lshrrev_b32_e32 v95, 2, v186
	v_and_b32_e32 v96, 3, v186
	v_mov_b32_e32 v97, 272
	v_mul_u32_u24_e32 v98, v186, v97
	v_lshl_add_u32 v246, v94, 4, v98
	v_lshl_add_u32 v190, v94, 3, v98
	v_mov_b32_e32 v97, 288
	v_mul_u32_u24_e32 v98, v186, v97
	v_lshl_add_u32 v244, v94, 4, v98
	v_lshl_add_u32 v99, v94, 2, v95
	v_mul_u32_u24_e32 v242, v99, v97
	v_lshl_add_u32 v242, v96, 3, v242
	v_mov_b32_e32 v97, 144
	v_mul_u32_u24_e32 v191, v99, v97
	v_lshl_add_u32 v191, v96, 3, v191
	s_lshl_b32 s49, s36, 5
	v_add_u32_e32 v191, s49, v191
	v_lshlrev_b32_e32 v243, 4, v94
	v_add_u32_e32 v243, 0x21000, v243
	s_cmp_eq_u32 s31, 0
	s_cselect_b64 vcc, -1, 0
	v_sub_u32_e32 v99, 15, v186
	v_cndmask_b32_e32 v99, v99, v186, vcc
	v_lshlrev_b32_e32 v247, 11, v99
	v_lshl_add_u32 v247, v94, 3, v247
	v_add_u32_e32 v247, s49, v247
	s_lshl_b32 s52, s35, 1
	s_lshr_b32 s75, 0xa90f, s52
	s_and_b32 s75, s75, 3
	s_lshr_b32 s98, 0xa008, s52
	s_and_b32 s98, s98, 3
	s_lshr_b32 s99, 0xa50d, s52
	s_and_b32 s99, s99, 3
	v_lshlrev_b32_e32 v95, 2, v94
	v_cmp_gt_u32_e64 s[92:93], v95, v186
	s_nop 1
	s_cmp_eq_u32 s98, s75
	s_cselect_b64 s[40:41], s[92:93], 0
	s_cmp_eq_u32 s99, s75
	s_cselect_b64 s[80:81], s[92:93], 0
	v_add_u32_e32 v96, 1, v95
	v_cmp_gt_u32_e64 s[92:93], v96, v186
	s_nop 1
	s_cmp_eq_u32 s98, s75
	s_cselect_b64 s[42:43], s[92:93], 0
	s_cmp_eq_u32 s99, s75
	s_cselect_b64 s[82:83], s[92:93], 0
	v_add_u32_e32 v96, 2, v95
	v_cmp_gt_u32_e64 s[92:93], v96, v186
	s_nop 1
	s_cmp_eq_u32 s98, s75
	s_cselect_b64 s[44:45], s[92:93], 0
	s_cmp_eq_u32 s99, s75
	s_cselect_b64 s[84:85], s[92:93], 0
	v_add_u32_e32 v96, 3, v95
	v_cmp_gt_u32_e64 s[92:93], v96, v186
	s_nop 1
	s_cmp_eq_u32 s98, s75
	s_cselect_b64 s[46:47], s[92:93], 0
	s_cmp_eq_u32 s99, s75
	s_cselect_b64 s[86:87], s[92:93], 0
	s_mul_i32 s52, s99, 4608
	v_add_u32_e32 v245, s52, v244
	s_mul_i32 s52, s98, 4608
	v_add_u32_e32 v244, s52, v244
	s_mul_i32 s52, s75, 4352
	v_add_u32_e32 v246, s52, v246
	v_mov_b32_e32 v97, 160
	v_mul_u32_u24_e32 v59, v186, v97
	v_lshl_add_u32 v59, v94, 4, v59
	v_add_u32_e32 v59, 0x21600, v59
	s_mul_i32 s52, s75, 2560
	s_lshr_b32 s53, s98, 1
	s_lshl_b32 s53, s53, 6
	s_add_i32 s53, s53, s52
	s_and_b32 s64, s98, 1
	s_lshl_b32 s64, s64, 3
	s_add_i32 s53, s53, s64
	v_add_u32_e32 v57, s53, v59
	s_lshr_b32 s53, s99, 1
	s_lshl_b32 s53, s53, 6
	s_add_i32 s53, s53, s52
	s_and_b32 s64, s99, 1
	s_lshl_b32 s64, s64, 3
	s_add_i32 s53, s53, s64
	v_add_u32_e32 v58, s53, v59
	v_lshlrev_b32_e32 v96, 4, v0
	v_add_u32_e32 v96, 0x21600, v96
	v_mov_b32_e32 v42, 0
	v_mov_b32_e32 v43, 0
	v_mov_b32_e32 v44, 0
	v_mov_b32_e32 v45, 0
	ds_write_b128 v96, v[42:45]
	s_cmp_gt_u32 s35, 1
	s_cbranch_scc1 .Lp8_alz
	ds_write_b128 v96, v[42:45] offset:8192
.Lp8_alz:
	s_mov_b32 s94, 0
	v_and_b32_e32 v95, 63, v0
	s_add_i32 s5, s35, 0
	s_cmp_ge_u32 s5, 17
	s_cselect_b32 s6, 1, 0
	s_cmp_ge_u32 s5, 35
	s_cselect_b32 s7, 1, 0
	s_add_i32 s6, s6, s7
	s_lshl_b32 s7, s6, 0
	s_or_b32 s94, s94, s7
	s_cmp_eq_u32 s6, 0
	s_cselect_b32 s48, 0, 1088
	s_cselect_b32 s49, 17, 18
	s_mov_b32 s7, 238609295
	s_cselect_b32 s52, 252645136, s7
	s_mov_b32 s53, 16
	s_mov_b32 s64, s30
	s_cmp_eq_u32 s6, 2
	s_cselect_b32 s48, 2240, s48
	s_cselect_b32 s49, 9, s49
	s_cselect_b32 s52, 477218589, s52
	s_cselect_b32 s53, 8, s53
	s_cselect_b32 s64, 0x1800, s64
	s_lshl_b32 s5, s5, 6
	s_sub_i32 s5, s5, s48
	v_add_u32_e32 v96, s5, v95
	v_mul_hi_u32 v97, v96, s52
	v_mul_lo_u32 v98, v97, s49
	v_sub_u32_e32 v98, v96, v98
	v_cmp_gt_u32_e64 vcc, s53, v98
	s_nop 1
	v_cndmask_b32_e32 v98, 0, v98, vcc
	v_sub_u32_e32 v99, 63, v97
	s_cmp_eq_u32 s31, 0
	s_cselect_b64 vcc, -1, 0
	v_cndmask_b32_e32 v99, v99, v97, vcc
	v_mul_lo_u32 v99, v99, s64
	v_lshl_add_u32 v232, v98, 4, v99
	s_add_i32 s5, s35, 8
	s_cmp_ge_u32 s5, 17
	s_cselect_b32 s6, 1, 0
	s_cmp_ge_u32 s5, 35
	s_cselect_b32 s7, 1, 0
	s_add_i32 s6, s6, s7
	s_lshl_b32 s7, s6, 2
	s_or_b32 s94, s94, s7
	s_cmp_eq_u32 s6, 0
	s_cselect_b32 s48, 0, 1088
	s_cselect_b32 s49, 17, 18
	s_mov_b32 s7, 238609295
	s_cselect_b32 s52, 252645136, s7
	s_mov_b32 s53, 16
	s_mov_b32 s64, s30
	s_cmp_eq_u32 s6, 2
	s_cselect_b32 s48, 2240, s48
	s_cselect_b32 s49, 9, s49
	s_cselect_b32 s52, 477218589, s52
	s_cselect_b32 s53, 8, s53
	s_cselect_b32 s64, 0x1800, s64
	s_lshl_b32 s5, s5, 6
	s_sub_i32 s5, s5, s48
	v_add_u32_e32 v96, s5, v95
	v_mul_hi_u32 v97, v96, s52
	v_mul_lo_u32 v98, v97, s49
	v_sub_u32_e32 v98, v96, v98
	v_cmp_gt_u32_e64 vcc, s53, v98
	s_nop 1
	v_cndmask_b32_e32 v98, 0, v98, vcc
	v_sub_u32_e32 v99, 63, v97
	s_cmp_eq_u32 s31, 0
	s_cselect_b64 vcc, -1, 0
	v_cndmask_b32_e32 v99, v99, v97, vcc
	v_mul_lo_u32 v99, v99, s64
	v_lshl_add_u32 v233, v98, 4, v99
	s_add_i32 s5, s35, 16
	s_cmp_ge_u32 s5, 17
	s_cselect_b32 s6, 1, 0
	s_cmp_ge_u32 s5, 35
	s_cselect_b32 s7, 1, 0
	s_add_i32 s6, s6, s7
	s_lshl_b32 s7, s6, 4
	s_or_b32 s94, s94, s7
	s_cmp_eq_u32 s6, 0
	s_cselect_b32 s48, 0, 1088
	s_cselect_b32 s49, 17, 18
	s_mov_b32 s7, 238609295
	s_cselect_b32 s52, 252645136, s7
	s_mov_b32 s53, 16
	s_mov_b32 s64, s30
	s_cmp_eq_u32 s6, 2
	s_cselect_b32 s48, 2240, s48
	s_cselect_b32 s49, 9, s49
	s_cselect_b32 s52, 477218589, s52
	s_cselect_b32 s53, 8, s53
	s_cselect_b32 s64, 0x1800, s64
	s_lshl_b32 s5, s5, 6
	s_sub_i32 s5, s5, s48
	v_add_u32_e32 v96, s5, v95
	v_mul_hi_u32 v97, v96, s52
	v_mul_lo_u32 v98, v97, s49
	v_sub_u32_e32 v98, v96, v98
	v_cmp_gt_u32_e64 vcc, s53, v98
	s_nop 1
	v_cndmask_b32_e32 v98, 0, v98, vcc
	v_sub_u32_e32 v99, 63, v97
	s_cmp_eq_u32 s31, 0
	s_cselect_b64 vcc, -1, 0
	v_cndmask_b32_e32 v99, v99, v97, vcc
	v_mul_lo_u32 v99, v99, s64
	v_lshl_add_u32 v234, v98, 4, v99
	s_add_i32 s5, s35, 24
	s_cmp_ge_u32 s5, 17
	s_cselect_b32 s6, 1, 0
	s_cmp_ge_u32 s5, 35
	s_cselect_b32 s7, 1, 0
	s_add_i32 s6, s6, s7
	s_lshl_b32 s7, s6, 6
	s_or_b32 s94, s94, s7
	s_cmp_eq_u32 s6, 0
	s_cselect_b32 s48, 0, 1088
	s_cselect_b32 s49, 17, 18
	s_mov_b32 s7, 238609295
	s_cselect_b32 s52, 252645136, s7
	s_mov_b32 s53, 16
	s_mov_b32 s64, s30
	s_cmp_eq_u32 s6, 2
	s_cselect_b32 s48, 2240, s48
	s_cselect_b32 s49, 9, s49
	s_cselect_b32 s52, 477218589, s52
	s_cselect_b32 s53, 8, s53
	s_cselect_b32 s64, 0x1800, s64
	s_lshl_b32 s5, s5, 6
	s_sub_i32 s5, s5, s48
	v_add_u32_e32 v96, s5, v95
	v_mul_hi_u32 v97, v96, s52
	v_mul_lo_u32 v98, v97, s49
	v_sub_u32_e32 v98, v96, v98
	v_cmp_gt_u32_e64 vcc, s53, v98
	s_nop 1
	v_cndmask_b32_e32 v98, 0, v98, vcc
	v_sub_u32_e32 v99, 63, v97
	s_cmp_eq_u32 s31, 0
	s_cselect_b64 vcc, -1, 0
	v_cndmask_b32_e32 v99, v99, v97, vcc
	v_mul_lo_u32 v99, v99, s64
	v_lshl_add_u32 v235, v98, 4, v99
	s_add_i32 s5, s35, 32
	s_cmp_ge_u32 s5, 17
	s_cselect_b32 s6, 1, 0
	s_cmp_ge_u32 s5, 35
	s_cselect_b32 s7, 1, 0
	s_add_i32 s6, s6, s7
	s_lshl_b32 s7, s6, 8
	s_or_b32 s94, s94, s7
	s_cmp_eq_u32 s6, 0
	s_cselect_b32 s48, 0, 1088
	s_cselect_b32 s49, 17, 18
	s_mov_b32 s7, 238609295
	s_cselect_b32 s52, 252645136, s7
	s_mov_b32 s53, 16
	s_mov_b32 s64, s30
	s_cmp_eq_u32 s6, 2
	s_cselect_b32 s48, 2240, s48
	s_cselect_b32 s49, 9, s49
	s_cselect_b32 s52, 477218589, s52
	s_cselect_b32 s53, 8, s53
	s_cselect_b32 s64, 0x1800, s64
	s_lshl_b32 s5, s5, 6
	s_sub_i32 s5, s5, s48
	v_add_u32_e32 v96, s5, v95
	v_mul_hi_u32 v97, v96, s52
	v_mul_lo_u32 v98, v97, s49
	v_sub_u32_e32 v98, v96, v98
	v_cmp_gt_u32_e64 vcc, s53, v98
	s_nop 1
	v_cndmask_b32_e32 v98, 0, v98, vcc
	v_sub_u32_e32 v99, 63, v97
	s_cmp_eq_u32 s31, 0
	s_cselect_b64 vcc, -1, 0
	v_cndmask_b32_e32 v99, v99, v97, vcc
	v_mul_lo_u32 v99, v99, s64
	v_lshl_add_u32 v236, v98, 4, v99
	s_add_i32 s5, s35, 40
	s_cmp_ge_u32 s5, 17
	s_cselect_b32 s6, 1, 0
	s_cmp_ge_u32 s5, 35
	s_cselect_b32 s7, 1, 0
	s_add_i32 s6, s6, s7
	s_lshl_b32 s7, s6, 10
	s_or_b32 s94, s94, s7
	s_cmp_eq_u32 s6, 0
	s_cselect_b32 s48, 0, 1088
	s_cselect_b32 s49, 17, 18
	s_mov_b32 s7, 238609295
	s_cselect_b32 s52, 252645136, s7
	s_mov_b32 s53, 16
	s_mov_b32 s64, s30
	s_cmp_eq_u32 s6, 2
	s_cselect_b32 s48, 2240, s48
	s_cselect_b32 s49, 9, s49
	s_cselect_b32 s52, 477218589, s52
	s_cselect_b32 s53, 8, s53
	s_cselect_b32 s64, 0x1800, s64
	s_lshl_b32 s5, s5, 6
	s_sub_i32 s5, s5, s48
	v_add_u32_e32 v96, s5, v95
	v_mul_hi_u32 v97, v96, s52
	v_mul_lo_u32 v98, v97, s49
	v_sub_u32_e32 v98, v96, v98
	v_cmp_gt_u32_e64 vcc, s53, v98
	s_nop 1
	v_cndmask_b32_e32 v98, 0, v98, vcc
	v_sub_u32_e32 v99, 63, v97
	s_cmp_eq_u32 s31, 0
	s_cselect_b64 vcc, -1, 0
	v_cndmask_b32_e32 v99, v99, v97, vcc
	v_mul_lo_u32 v99, v99, s64
	v_lshl_add_u32 v237, v98, 4, v99
	v_mov_b32_e32 v2, 0
	v_mov_b32_e32 v3, 0
	v_mov_b32_e32 v4, 0
	v_mov_b32_e32 v5, 0
	v_mov_b32_e32 v6, 0
	v_mov_b32_e32 v7, 0
	v_mov_b32_e32 v8, 0
	v_mov_b32_e32 v9, 0
	v_mov_b32_e32 v10, 0
	v_mov_b32_e32 v11, 0
	v_mov_b32_e32 v12, 0
	v_mov_b32_e32 v13, 0
	v_mov_b32_e32 v14, 0
	v_mov_b32_e32 v15, 0
	v_mov_b32_e32 v16, 0
	v_mov_b32_e32 v17, 0
	v_mov_b32_e32 v18, 0
	v_mov_b32_e32 v19, 0
	v_mov_b32_e32 v20, 0
	v_mov_b32_e32 v21, 0
	v_mov_b32_e32 v22, 0
	v_mov_b32_e32 v23, 0
	v_mov_b32_e32 v24, 0
	v_mov_b32_e32 v25, 0
	v_mov_b32_e32 v26, 0
	v_mov_b32_e32 v27, 0
	v_mov_b32_e32 v28, 0
	v_mov_b32_e32 v29, 0
	v_mov_b32_e32 v30, 0
	v_mov_b32_e32 v31, 0
	v_mov_b32_e32 v32, 0
	v_mov_b32_e32 v33, 0
	s_mov_b32 s12, 0
	s_mov_b32 s100, 0
	s_cmp_eq_u32 s37, 0
	s_cbranch_scc0 .Lp8_pro1
	s_add_i32 s64, s12, 0
	s_min_u32 s65, s64, 35
	s_sub_i32 s48, 3, s65
	s_sub_i32 s49, 39, s65
	s_cmp_lt_u32 s65, 4
	s_cselect_b32 s48, s48, s49
	s_cmp_eq_u32 s31, 0
	s_cselect_b32 s54, s65, s48
	s_lshl_b32 s48, s54, 6
	s_add_i32 s49, s33, s48
	s_add_i32 s48, s34, s48
	s_cmp_lt_u32 s54, 4
	s_cselect_b32 s55, s49, s48
	s_mul_i32 s0, s55, s30
	s_mul_i32 s1, s55, 0x1800
	s_add_i32 s5, s100, 0
	s_sub_i32 s6, s5, 3
	s_cmp_ge_u32 s5, 3
	s_cselect_b32 s5, s6, s5
	s_mul_i32 s14, s5, 0xb000
	s_lshl_b32 s4, s5, 9
	s_add_i32 s14, s14, s95
	s_add_u32 s56, s16, s0
	s_addc_u32 s57, s17, 0
	s_add_u32 s58, s18, s0
	s_addc_u32 s59, s19, 0
	s_add_u32 s60, s20, s1
	s_addc_u32 s61, s21, 0
	s_add_i32 s7, s14, 0
	s_mov_b32 m0, s7
	s_nop 0
	global_load_lds_dwordx4 v232, s[56:57]
	s_add_i32 s7, s14, 8192
	s_mov_b32 m0, s7
	s_nop 0
	global_load_lds_dwordx4 v233, s[56:57]
	s_cmp_eq_u32 s35, 0
	s_cselect_b64 s[2:3], s[56:57], s[58:59]
	s_add_i32 s7, s14, 16384
	s_mov_b32 m0, s7
	s_nop 0
	global_load_lds_dwordx4 v234, s[2:3]
	s_add_i32 s7, s14, 24576
	s_mov_b32 m0, s7
	s_nop 0
	global_load_lds_dwordx4 v235, s[58:59]
	s_cmp_lt_u32 s35, 3
	s_cselect_b64 s[2:3], s[58:59], s[60:61]
	s_add_i32 s7, s14, 32768
	s_mov_b32 m0, s7
	s_nop 0
	global_load_lds_dwordx4 v236, s[2:3]
	s_add_i32 s7, s14, 40960
	s_mov_b32 m0, s7
	s_nop 0
	global_load_lds_dwordx4 v237, s[60:61]
	s_cmp_gt_u32 s35, 1
	s_cbranch_scc1 .Lp8_nodec_2
	s_lshl_b32 s5, s54, 9
	s_add_u32 s2, s22, s5
	s_addc_u32 s3, s23, 0
	s_lshr_b32 s6, s95, 2
	s_add_i32 s6, s6, s4
	s_add_i32 s6, s6, 0x21000
	s_mov_b32 m0, s6
	s_nop 0
	global_load_lds_dword v194, s[2:3]
.Lp8_nodec_2:
	s_add_i32 s64, s12, 1
	s_min_u32 s65, s64, 35
	s_sub_i32 s48, 3, s65
	s_sub_i32 s49, 39, s65
	s_cmp_lt_u32 s65, 4
	s_cselect_b32 s48, s48, s49
	s_cmp_eq_u32 s31, 0
	s_cselect_b32 s54, s65, s48
	s_lshl_b32 s48, s54, 6
	s_add_i32 s49, s33, s48
	s_add_i32 s48, s34, s48
	s_cmp_lt_u32 s54, 4
	s_cselect_b32 s55, s49, s48
	s_mul_i32 s0, s55, s30
	s_mul_i32 s1, s55, 0x1800
	s_add_i32 s5, s100, 1
	s_sub_i32 s6, s5, 3
	s_cmp_ge_u32 s5, 3
	s_cselect_b32 s5, s6, s5
	s_mul_i32 s14, s5, 0xb000
	s_lshl_b32 s4, s5, 9
	s_add_i32 s14, s14, s95
	s_add_u32 s56, s16, s0
	s_addc_u32 s57, s17, 0
	s_add_u32 s58, s18, s0
	s_addc_u32 s59, s19, 0
	s_add_u32 s60, s20, s1
	s_addc_u32 s61, s21, 0
	s_add_i32 s7, s14, 0
	s_mov_b32 m0, s7
	s_nop 0
	global_load_lds_dwordx4 v232, s[56:57]
	s_add_i32 s7, s14, 8192
	s_mov_b32 m0, s7
	s_nop 0
	global_load_lds_dwordx4 v233, s[56:57]
	s_cmp_eq_u32 s35, 0
	s_cselect_b64 s[2:3], s[56:57], s[58:59]
	s_add_i32 s7, s14, 16384
	s_mov_b32 m0, s7
	s_nop 0
	global_load_lds_dwordx4 v234, s[2:3]
	s_add_i32 s7, s14, 24576
	s_mov_b32 m0, s7
	s_nop 0
	global_load_lds_dwordx4 v235, s[58:59]
	s_cmp_lt_u32 s35, 3
	s_cselect_b64 s[2:3], s[58:59], s[60:61]
	s_add_i32 s7, s14, 32768
	s_mov_b32 m0, s7
	s_nop 0
	global_load_lds_dwordx4 v236, s[2:3]
	s_add_i32 s7, s14, 40960
	s_mov_b32 m0, s7
	s_nop 0
	global_load_lds_dwordx4 v237, s[60:61]
	s_cmp_gt_u32 s35, 1
	s_cbranch_scc1 .Lp8_nodec_4
	s_lshl_b32 s5, s54, 9
	s_add_u32 s2, s22, s5
	s_addc_u32 s3, s23, 0
	s_lshr_b32 s6, s95, 2
	s_add_i32 s6, s6, s4
	s_add_i32 s6, s6, 0x21000
	s_mov_b32 m0, s6
	s_nop 0
	global_load_lds_dword v194, s[2:3]

.Lp8_pro1:
	s_add_i32 s64, s12, 0
	s_min_u32 s65, s64, 35
	s_sub_i32 s48, 3, s65
	s_sub_i32 s49, 39, s65
	s_cmp_lt_u32 s65, 4
	s_cselect_b32 s48, s48, s49
	s_cmp_eq_u32 s31, 0
	s_cselect_b32 s54, s65, s48
	s_lshl_b32 s48, s54, 6
	s_add_i32 s49, s33, s48
	s_add_i32 s48, s34, s48
	s_cmp_lt_u32 s54, 4
	s_cselect_b32 s55, s49, s48
	s_mul_i32 s0, s55, s30
	s_mul_i32 s1, s55, 0x1800
	s_add_i32 s5, s100, 0
	s_sub_i32 s6, s5, 3
	s_cmp_ge_u32 s5, 3
	s_cselect_b32 s5, s6, s5
	s_mul_i32 s14, s5, 0xb000
	s_lshl_b32 s4, s5, 9
	s_add_i32 s14, s14, s95
	s_add_u32 s56, s16, s0
	s_addc_u32 s57, s17, 0
	s_add_u32 s58, s18, s0
	s_addc_u32 s59, s19, 0
	s_add_u32 s60, s20, s1
	s_addc_u32 s61, s21, 0
	s_add_i32 s7, s14, 0
	s_mov_b32 m0, s7
	s_nop 0
	global_load_lds_dwordx4 v232, s[56:57]
	s_add_i32 s7, s14, 8192
	s_mov_b32 m0, s7
	s_nop 0
	global_load_lds_dwordx4 v233, s[56:57]
	s_cmp_eq_u32 s35, 0
	s_cselect_b64 s[2:3], s[56:57], s[58:59]
	s_add_i32 s7, s14, 16384
	s_mov_b32 m0, s7
	s_nop 0
	global_load_lds_dwordx4 v234, s[2:3]
	s_add_i32 s7, s14, 24576
	s_mov_b32 m0, s7
	s_nop 0
	global_load_lds_dwordx4 v235, s[58:59]
	s_cmp_lt_u32 s35, 3
	s_cselect_b64 s[2:3], s[58:59], s[60:61]
	s_add_i32 s7, s14, 32768
	s_mov_b32 m0, s7
	s_nop 0
	global_load_lds_dwordx4 v236, s[2:3]
	s_add_i32 s64, s12, 1
	s_min_u32 s65, s64, 35
	s_sub_i32 s48, 3, s65
	s_sub_i32 s49, 39, s65
	s_cmp_lt_u32 s65, 4
	s_cselect_b32 s48, s48, s49
	s_cmp_eq_u32 s31, 0
	s_cselect_b32 s54, s65, s48
	s_lshl_b32 s48, s54, 6
	s_add_i32 s49, s33, s48
	s_add_i32 s48, s34, s48
	s_cmp_lt_u32 s54, 4
	s_cselect_b32 s55, s49, s48
	s_mul_i32 s0, s55, s30
	s_mul_i32 s1, s55, 0x1800
	s_add_i32 s5, s100, 1
	s_sub_i32 s6, s5, 3
	s_cmp_ge_u32 s5, 3
	s_cselect_b32 s5, s6, s5
	s_mul_i32 s14, s5, 0xb000
	s_lshl_b32 s4, s5, 9
	s_add_i32 s14, s14, s95
	s_add_u32 s56, s16, s0
	s_addc_u32 s57, s17, 0
	s_add_u32 s58, s18, s0
	s_addc_u32 s59, s19, 0
	s_add_u32 s60, s20, s1
	s_addc_u32 s61, s21, 0
	s_add_i32 s7, s14, 0
	s_mov_b32 m0, s7
	s_nop 0
	global_load_lds_dwordx4 v232, s[56:57]
	s_add_i32 s7, s14, 8192
	s_mov_b32 m0, s7
	s_nop 0
	global_load_lds_dwordx4 v233, s[56:57]
	s_cmp_eq_u32 s35, 0
	s_cselect_b64 s[2:3], s[56:57], s[58:59]
	s_add_i32 s7, s14, 16384
	s_mov_b32 m0, s7
	s_nop 0
	global_load_lds_dwordx4 v234, s[2:3]
	s_add_i32 s7, s14, 24576
	s_mov_b32 m0, s7
	s_nop 0
	global_load_lds_dwordx4 v235, s[58:59]
	s_cmp_lt_u32 s35, 3
	s_cselect_b64 s[2:3], s[58:59], s[60:61]
	s_add_i32 s7, s14, 32768
	s_mov_b32 m0, s7
	s_nop 0
	global_load_lds_dwordx4 v236, s[2:3]
.Lp8_pro:
	s_waitcnt vmcnt(0) lgkmcnt(0)
	s_barrier
.Lp8_step:
	s_mul_i32 s13, s100, 0xb000
	s_lshl_b32 s4, s100, 9
	v_add_u32_e32 v183, s13, v190
	v_add_u32_e32 v184, s13, v191
	v_add_u32_e32 v185, s13, v242
	v_add_u32_e32 v54, s13, v244
	v_add_u32_e32 v55, s13, v245
	v_add_u32_e32 v56, s13, v246
	v_add_u32_e32 v188, s4, v243
	s_cmp_lt_u32 s12, 4
	s_nop 0
	s_cbranch_scc0 .Lp8_lat
	s_cmp_eq_u32 s37, 0
	s_cbranch_scc0 .Lp8_ctx1
	ds_read_b64_tr_b16 v[126:127], v184 offset:35840
	ds_read_b64_tr_b16 v[128:129], v184 offset:38144
	ds_read_b64_tr_b16 v[130:131], v184 offset:40448
	ds_read_b64_tr_b16 v[132:133], v184 offset:42752
	ds_read_b64_tr_b16 v[62:63], v185 offset:17408
	ds_read_b64_tr_b16 v[64:65], v185 offset:22016
	ds_read_b64_tr_b16 v[66:67], v185 offset:26624
	ds_read_b64_tr_b16 v[68:69], v185 offset:31232
	ds_read_b64_tr_b16 v[70:71], v185 offset:17440
	ds_read_b64_tr_b16 v[72:73], v185 offset:22048
	ds_read_b64_tr_b16 v[74:75], v185 offset:26656
	ds_read_b64_tr_b16 v[76:77], v185 offset:31264
	ds_read_b64_tr_b16 v[78:79], v185 offset:17472
	ds_read_b64_tr_b16 v[80:81], v185 offset:22080
	ds_read_b64_tr_b16 v[82:83], v185 offset:26688
	ds_read_b64_tr_b16 v[84:85], v185 offset:31296
	ds_read_b64_tr_b16 v[86:87], v185 offset:17504
	ds_read_b64_tr_b16 v[88:89], v185 offset:22112
	ds_read_b64_tr_b16 v[90:91], v185 offset:26720
	ds_read_b64_tr_b16 v[92:93], v185 offset:31328
	ds_read_b64_tr_b16 v[134:135], v185 offset:17536
	ds_read_b64_tr_b16 v[136:137], v185 offset:22144
	ds_read_b64_tr_b16 v[138:139], v185 offset:26752
	ds_read_b64_tr_b16 v[140:141], v185 offset:31360
	ds_read_b64_tr_b16 v[142:143], v185 offset:17568
	ds_read_b64_tr_b16 v[144:145], v185 offset:22176
	ds_read_b64_tr_b16 v[146:147], v185 offset:26784
	ds_read_b64_tr_b16 v[148:149], v185 offset:31392
	ds_read_b64_tr_b16 v[216:217], v185 offset:17600
	ds_read_b64_tr_b16 v[218:219], v185 offset:22208
	ds_read_b64_tr_b16 v[220:221], v185 offset:26816
	ds_read_b64_tr_b16 v[222:223], v185 offset:31424
	ds_read_b64_tr_b16 v[224:225], v185 offset:17632
	ds_read_b64_tr_b16 v[226:227], v185 offset:22240
	ds_read_b64_tr_b16 v[228:229], v185 offset:26848
	ds_read_b64_tr_b16 v[230:231], v185 offset:31456
	ds_read_b128 v[166:169], v188 offset:0
	ds_read_b128 v[170:173], v188 offset:64
	ds_read_b128 v[174:177], v188 offset:128
	ds_read_b128 v[178:181], v188 offset:192
	ds_read_b128 v[200:203], v188 offset:256
	ds_read_b128 v[204:207], v188 offset:320
	ds_read_b128 v[208:211], v188 offset:384
	ds_read_b128 v[212:215], v188 offset:448
	s_add_i32 s64, s12, 2
	s_min_u32 s65, s64, 35
	s_sub_i32 s48, 3, s65
	s_sub_i32 s49, 39, s65
	s_cmp_lt_u32 s65, 4
	s_cselect_b32 s48, s48, s49
	s_cmp_eq_u32 s31, 0
	s_cselect_b32 s54, s65, s48
	s_lshl_b32 s48, s54, 6
	s_add_i32 s49, s33, s48
	s_add_i32 s48, s34, s48
	s_cmp_lt_u32 s54, 4
	s_cselect_b32 s55, s49, s48
	s_mul_i32 s0, s55, s30
	s_mul_i32 s1, s55, 0x1800
	s_add_i32 s5, s100, 2
	s_sub_i32 s6, s5, 3
	s_cmp_ge_u32 s5, 3
	s_cselect_b32 s5, s6, s5
	s_mul_i32 s14, s5, 0xb000
	s_lshl_b32 s4, s5, 9
	s_add_i32 s14, s14, s95
	s_add_u32 s56, s16, s0
	s_addc_u32 s57, s17, 0
	s_add_u32 s58, s18, s0
	s_addc_u32 s59, s19, 0
	s_add_u32 s60, s20, s1
	s_addc_u32 s61, s21, 0
	s_add_i32 s7, s14, 0
	s_mov_b32 m0, s7
	s_nop 0
	global_load_lds_dwordx4 v232, s[56:57]
	s_add_i32 s7, s14, 8192
	s_mov_b32 m0, s7
	s_nop 0
	global_load_lds_dwordx4 v233, s[56:57]
	s_cmp_eq_u32 s35, 0
	s_cselect_b64 s[2:3], s[56:57], s[58:59]
	s_add_i32 s7, s14, 16384
	s_mov_b32 m0, s7
	s_nop 0
	global_load_lds_dwordx4 v234, s[2:3]
	s_add_i32 s7, s14, 24576
	s_mov_b32 m0, s7
	s_nop 0
	global_load_lds_dwordx4 v235, s[58:59]
	s_cmp_lt_u32 s35, 3
	s_cselect_b64 s[2:3], s[58:59], s[60:61]
	s_add_i32 s7, s14, 32768
	s_mov_b32 m0, s7
	s_nop 0
	global_load_lds_dwordx4 v236, s[2:3]
	s_add_i32 s7, s14, 40960
	s_mov_b32 m0, s7
	s_nop 0
	global_load_lds_dwordx4 v237, s[60:61]
	s_cmp_gt_u32 s35, 1
	s_cbranch_scc1 .Lp8_nodec_8
	s_lshl_b32 s5, s54, 9
	s_add_u32 s2, s22, s5
	s_addc_u32 s3, s23, 0
	s_lshr_b32 s6, s95, 2
	s_add_i32 s6, s6, s4
	s_add_i32 s6, s6, 0x21000
	s_mov_b32 m0, s6
	s_nop 0
	global_load_lds_dword v194, s[2:3]
.Lp8_nodec_8:
	s_waitcnt lgkmcnt(8)
	v_mfma_f32_16x16x32_bf16 v[2:5], v[62:65], v[126:129], v[2:5]
	v_mfma_f32_16x16x32_bf16 v[2:5], v[66:69], v[130:133], v[2:5]
	v_mfma_f32_16x16x32_bf16 v[6:9], v[70:73], v[126:129], v[6:9]
	v_mfma_f32_16x16x32_bf16 v[6:9], v[74:77], v[130:133], v[6:9]
	v_mfma_f32_16x16x32_bf16 v[10:13], v[78:81], v[126:129], v[10:13]
	v_mfma_f32_16x16x32_bf16 v[10:13], v[82:85], v[130:133], v[10:13]
	v_mfma_f32_16x16x32_bf16 v[14:17], v[86:89], v[126:129], v[14:17]
	v_mfma_f32_16x16x32_bf16 v[14:17], v[90:93], v[130:133], v[14:17]
	v_mfma_f32_16x16x32_bf16 v[18:21], v[134:137], v[126:129], v[18:21]
	v_mfma_f32_16x16x32_bf16 v[18:21], v[138:141], v[130:133], v[18:21]
	v_mfma_f32_16x16x32_bf16 v[22:25], v[142:145], v[126:129], v[22:25]
	v_mfma_f32_16x16x32_bf16 v[22:25], v[146:149], v[130:133], v[22:25]
	v_mfma_f32_16x16x32_bf16 v[26:29], v[216:219], v[126:129], v[26:29]
	v_mfma_f32_16x16x32_bf16 v[26:29], v[220:223], v[130:133], v[26:29]
	v_mfma_f32_16x16x32_bf16 v[30:33], v[224:227], v[126:129], v[30:33]
	v_mfma_f32_16x16x32_bf16 v[30:33], v[228:231], v[130:133], v[30:33]
	s_waitcnt lgkmcnt(0)
	v_pk_mul_f32 v[2:3], v[2:3], v[166:167]
	v_pk_mul_f32 v[4:5], v[4:5], v[168:169]
	v_pk_mul_f32 v[6:7], v[6:7], v[170:171]
	v_pk_mul_f32 v[8:9], v[8:9], v[172:173]
	v_pk_mul_f32 v[10:11], v[10:11], v[174:175]
	v_pk_mul_f32 v[12:13], v[12:13], v[176:177]
	v_pk_mul_f32 v[14:15], v[14:15], v[178:179]
	v_pk_mul_f32 v[16:17], v[16:17], v[180:181]
	v_pk_mul_f32 v[18:19], v[18:19], v[200:201]
	v_pk_mul_f32 v[20:21], v[20:21], v[202:203]
	v_pk_mul_f32 v[22:23], v[22:23], v[204:205]
	v_pk_mul_f32 v[24:25], v[24:25], v[206:207]
	v_pk_mul_f32 v[26:27], v[26:27], v[208:209]
	v_pk_mul_f32 v[28:29], v[28:29], v[210:211]
	v_pk_mul_f32 v[30:31], v[30:31], v[212:213]
	v_pk_mul_f32 v[32:33], v[32:33], v[214:215]
	s_waitcnt vmcnt(6)
	s_nop 0
	s_barrier
	s_branch .Lp8_next
.Lp8_ctx1:
	ds_read_b64_tr_b16 v[126:127], v184 offset:35840
	ds_read_b64_tr_b16 v[128:129], v184 offset:38144
	ds_read_b64_tr_b16 v[130:131], v184 offset:40448
	ds_read_b64_tr_b16 v[132:133], v184 offset:42752
	ds_read_b64_tr_b16 v[62:63], v185 offset:17408
	ds_read_b64_tr_b16 v[64:65], v185 offset:22016
	ds_read_b64_tr_b16 v[66:67], v185 offset:26624
	ds_read_b64_tr_b16 v[68:69], v185 offset:31232
	ds_read_b64_tr_b16 v[70:71], v185 offset:17440
	ds_read_b64_tr_b16 v[72:73], v185 offset:22048
	ds_read_b64_tr_b16 v[74:75], v185 offset:26656
	ds_read_b64_tr_b16 v[76:77], v185 offset:31264
	ds_read_b64_tr_b16 v[78:79], v185 offset:17472
	ds_read_b64_tr_b16 v[80:81], v185 offset:22080
	ds_read_b64_tr_b16 v[82:83], v185 offset:26688
	ds_read_b64_tr_b16 v[84:85], v185 offset:31296
	ds_read_b64_tr_b16 v[86:87], v185 offset:17504
	ds_read_b64_tr_b16 v[88:89], v185 offset:22112
	ds_read_b64_tr_b16 v[90:91], v185 offset:26720
	ds_read_b64_tr_b16 v[92:93], v185 offset:31328
	ds_read_b64_tr_b16 v[134:135], v185 offset:17536
	ds_read_b64_tr_b16 v[136:137], v185 offset:22144
	ds_read_b64_tr_b16 v[138:139], v185 offset:26752
	ds_read_b64_tr_b16 v[140:141], v185 offset:31360
	ds_read_b64_tr_b16 v[142:143], v185 offset:17568
	ds_read_b64_tr_b16 v[144:145], v185 offset:22176
	ds_read_b64_tr_b16 v[146:147], v185 offset:26784
	ds_read_b64_tr_b16 v[148:149], v185 offset:31392
	ds_read_b64_tr_b16 v[216:217], v185 offset:17600
	ds_read_b64_tr_b16 v[218:219], v185 offset:22208
	ds_read_b64_tr_b16 v[220:221], v185 offset:26816
	ds_read_b64_tr_b16 v[222:223], v185 offset:31424
	ds_read_b64_tr_b16 v[224:225], v185 offset:17632
	ds_read_b64_tr_b16 v[226:227], v185 offset:22240
	ds_read_b64_tr_b16 v[228:229], v185 offset:26848
	ds_read_b64_tr_b16 v[230:231], v185 offset:31456
	ds_read_b128 v[166:169], v188 offset:0
	ds_read_b128 v[170:173], v188 offset:64
	ds_read_b128 v[174:177], v188 offset:128
	ds_read_b128 v[178:181], v188 offset:192
	ds_read_b128 v[200:203], v188 offset:256
	ds_read_b128 v[204:207], v188 offset:320
	ds_read_b128 v[208:211], v188 offset:384
	ds_read_b128 v[212:215], v188 offset:448
	s_add_i32 s64, s12, 2
	s_min_u32 s65, s64, 35
	s_sub_i32 s48, 3, s65
	s_sub_i32 s49, 39, s65
	s_cmp_lt_u32 s65, 4
	s_cselect_b32 s48, s48, s49
	s_cmp_eq_u32 s31, 0
	s_cselect_b32 s54, s65, s48
	s_lshl_b32 s48, s54, 6
	s_add_i32 s49, s33, s48
	s_add_i32 s48, s34, s48
	s_cmp_lt_u32 s54, 4
	s_cselect_b32 s55, s49, s48
	s_mul_i32 s0, s55, s30
	s_mul_i32 s1, s55, 0x1800
	s_add_i32 s5, s100, 2
	s_sub_i32 s6, s5, 3
	s_cmp_ge_u32 s5, 3
	s_cselect_b32 s5, s6, s5
	s_mul_i32 s14, s5, 0xb000
	s_lshl_b32 s4, s5, 9
	s_add_i32 s14, s14, s95
	s_add_u32 s56, s16, s0
	s_addc_u32 s57, s17, 0
	s_add_u32 s58, s18, s0
	s_addc_u32 s59, s19, 0
	s_add_u32 s60, s20, s1
	s_addc_u32 s61, s21, 0
	s_add_i32 s7, s14, 0
	s_mov_b32 m0, s7
	s_nop 0
	global_load_lds_dwordx4 v232, s[56:57]
	s_add_i32 s7, s14, 8192
	s_mov_b32 m0, s7
	s_nop 0
	global_load_lds_dwordx4 v233, s[56:57]
	s_cmp_eq_u32 s35, 0
	s_cselect_b64 s[2:3], s[56:57], s[58:59]
	s_add_i32 s7, s14, 16384
	s_mov_b32 m0, s7
	s_nop 0
	global_load_lds_dwordx4 v234, s[2:3]
	s_add_i32 s7, s14, 24576
	s_mov_b32 m0, s7
	s_nop 0
	global_load_lds_dwordx4 v235, s[58:59]
	s_cmp_lt_u32 s35, 3
	s_cselect_b64 s[2:3], s[58:59], s[60:61]
	s_add_i32 s7, s14, 32768
	s_mov_b32 m0, s7
	s_nop 0
	global_load_lds_dwordx4 v236, s[2:3]
	s_waitcnt lgkmcnt(8)
	v_mfma_f32_16x16x32_bf16 v[2:5], v[62:65], v[126:129], v[2:5]
	v_mfma_f32_16x16x32_bf16 v[2:5], v[66:69], v[130:133], v[2:5]
	v_mfma_f32_16x16x32_bf16 v[6:9], v[70:73], v[126:129], v[6:9]
	v_mfma_f32_16x16x32_bf16 v[6:9], v[74:77], v[130:133], v[6:9]
	v_mfma_f32_16x16x32_bf16 v[10:13], v[78:81], v[126:129], v[10:13]
	v_mfma_f32_16x16x32_bf16 v[10:13], v[82:85], v[130:133], v[10:13]
	v_mfma_f32_16x16x32_bf16 v[14:17], v[86:89], v[126:129], v[14:17]
	v_mfma_f32_16x16x32_bf16 v[14:17], v[90:93], v[130:133], v[14:17]
	v_mfma_f32_16x16x32_bf16 v[18:21], v[134:137], v[126:129], v[18:21]
	v_mfma_f32_16x16x32_bf16 v[18:21], v[138:141], v[130:133], v[18:21]
	v_mfma_f32_16x16x32_bf16 v[22:25], v[142:145], v[126:129], v[22:25]
	v_mfma_f32_16x16x32_bf16 v[22:25], v[146:149], v[130:133], v[22:25]
	v_mfma_f32_16x16x32_bf16 v[26:29], v[216:219], v[126:129], v[26:29]
	v_mfma_f32_16x16x32_bf16 v[26:29], v[220:223], v[130:133], v[26:29]
	v_mfma_f32_16x16x32_bf16 v[30:33], v[224:227], v[126:129], v[30:33]
	v_mfma_f32_16x16x32_bf16 v[30:33], v[228:231], v[130:133], v[30:33]
	s_waitcnt lgkmcnt(0)
	v_pk_mul_f32 v[2:3], v[2:3], v[166:167]
	v_pk_mul_f32 v[4:5], v[4:5], v[168:169]
	v_pk_mul_f32 v[6:7], v[6:7], v[170:171]
	v_pk_mul_f32 v[8:9], v[8:9], v[172:173]
	v_pk_mul_f32 v[10:11], v[10:11], v[174:175]
	v_pk_mul_f32 v[12:13], v[12:13], v[176:177]
	v_pk_mul_f32 v[14:15], v[14:15], v[178:179]
	v_pk_mul_f32 v[16:17], v[16:17], v[180:181]
	v_pk_mul_f32 v[18:19], v[18:19], v[200:201]
	v_pk_mul_f32 v[20:21], v[20:21], v[202:203]
	v_pk_mul_f32 v[22:23], v[22:23], v[204:205]
	v_pk_mul_f32 v[24:25], v[24:25], v[206:207]
	v_pk_mul_f32 v[26:27], v[26:27], v[208:209]
	v_pk_mul_f32 v[28:29], v[28:29], v[210:211]
	v_pk_mul_f32 v[30:31], v[30:31], v[212:213]
	v_pk_mul_f32 v[32:33], v[32:33], v[214:215]
	s_waitcnt vmcnt(5)
	s_nop 0
	s_barrier
	s_branch .Lp8_next
.Lp8_lat:
	s_cmp_eq_u32 s37, 0
	s_cbranch_scc0 .Lp8_lat1
	s_sub_i32 s48, 3, s12
	s_sub_i32 s49, 39, s12
	s_cmp_lt_u32 s12, 4
	s_cselect_b32 s48, s48, s49
	s_cmp_eq_u32 s31, 0
	s_cselect_b32 s54, s12, s48
	s_lshl_b32 s48, s54, 6
	s_add_i32 s49, s33, s48
	s_add_i32 s48, s34, s48
	s_cmp_lt_u32 s54, 4
	s_cselect_b32 s55, s49, s48
	s_add_i32 s48, s55, 0
	s_add_i32 s49, s55, 48
	s_cmp_eq_u32 s31, 0
	s_cselect_b32 s48, s48, s49
	s_lshl_b32 s48, s48, 11
	s_add_u32 s8, s28, s48
	s_addc_u32 s9, s29, 0
	s_add_i32 s48, s55, 48
	s_add_i32 s49, s55, 0
	s_cmp_eq_u32 s31, 0
	s_cselect_b32 s48, s48, s49
	s_lshl_b32 s48, s48, 11
	s_add_u32 s10, s28, s48
	s_addc_u32 s11, s29, 0
	v_cvt_pk_bf16_f32 v150, v2, v3
	v_cvt_pk_bf16_f32 v151, v4, v5
	v_cvt_pk_bf16_f32 v152, v6, v7
	v_cvt_pk_bf16_f32 v153, v8, v9
	v_cvt_pk_bf16_f32 v154, v10, v11
	v_cvt_pk_bf16_f32 v155, v12, v13
	v_cvt_pk_bf16_f32 v156, v14, v15
	v_cvt_pk_bf16_f32 v157, v16, v17
	v_cvt_pk_bf16_f32 v158, v18, v19
	v_cvt_pk_bf16_f32 v159, v20, v21
	v_cvt_pk_bf16_f32 v160, v22, v23
	v_cvt_pk_bf16_f32 v161, v24, v25
	v_cvt_pk_bf16_f32 v162, v26, v27
	v_cvt_pk_bf16_f32 v163, v28, v29
	v_cvt_pk_bf16_f32 v164, v30, v31
	v_cvt_pk_bf16_f32 v165, v32, v33
	ds_read_b64_tr_b16 v[126:127], v184 offset:35840
	ds_read_b64_tr_b16 v[128:129], v184 offset:38144
	ds_read_b64_tr_b16 v[130:131], v184 offset:40448
	ds_read_b64_tr_b16 v[132:133], v184 offset:42752
	ds_read_b64_tr_b16 v[62:63], v185 offset:17408
	ds_read_b64_tr_b16 v[64:65], v185 offset:22016
	ds_read_b64_tr_b16 v[66:67], v185 offset:26624
	ds_read_b64_tr_b16 v[68:69], v185 offset:31232
	ds_read_b64_tr_b16 v[70:71], v185 offset:17440
	ds_read_b64_tr_b16 v[72:73], v185 offset:22048
	ds_read_b64_tr_b16 v[74:75], v185 offset:26656
	ds_read_b64_tr_b16 v[76:77], v185 offset:31264
	ds_read_b64_tr_b16 v[78:79], v185 offset:17472
	ds_read_b64_tr_b16 v[80:81], v185 offset:22080
	ds_read_b64_tr_b16 v[82:83], v185 offset:26688
	ds_read_b64_tr_b16 v[84:85], v185 offset:31296
	ds_read_b64_tr_b16 v[86:87], v185 offset:17504
	ds_read_b64_tr_b16 v[88:89], v185 offset:22112
	ds_read_b64_tr_b16 v[90:91], v185 offset:26720
	ds_read_b64_tr_b16 v[92:93], v185 offset:31328
	ds_read_b64 v[94:95], v183 offset:0
	ds_read_b64 v[96:97], v183 offset:32
	ds_read_b64 v[98:99], v183 offset:64
	ds_read_b64 v[100:101], v183 offset:96
	ds_read_b64 v[102:103], v183 offset:128
	ds_read_b64 v[104:105], v183 offset:160
	ds_read_b64 v[106:107], v183 offset:192
	ds_read_b64 v[108:109], v183 offset:224
	ds_read_b64 v[110:111], v183 offset:13056
	ds_read_b64 v[112:113], v183 offset:13088
	ds_read_b64 v[114:115], v183 offset:13120
	ds_read_b64 v[116:117], v183 offset:13152
	ds_read_b64 v[118:119], v183 offset:13184
	ds_read_b64 v[120:121], v183 offset:13216
	ds_read_b64 v[122:123], v183 offset:13248
	ds_read_b64 v[124:125], v183 offset:13280
	ds_read_b64_tr_b16 v[134:135], v185 offset:17536
	ds_read_b64_tr_b16 v[136:137], v185 offset:22144
	ds_read_b64_tr_b16 v[138:139], v185 offset:26752
	ds_read_b64_tr_b16 v[140:141], v185 offset:31360
	ds_read_b64_tr_b16 v[142:143], v185 offset:17568
	ds_read_b64_tr_b16 v[144:145], v185 offset:22176
	ds_read_b64_tr_b16 v[146:147], v185 offset:26784
	ds_read_b64_tr_b16 v[148:149], v185 offset:31392
	ds_read_b64_tr_b16 v[216:217], v185 offset:17600
	ds_read_b64_tr_b16 v[218:219], v185 offset:22208
	ds_read_b64_tr_b16 v[220:221], v185 offset:26816
	ds_read_b64_tr_b16 v[222:223], v185 offset:31424
	ds_read_b64_tr_b16 v[224:225], v185 offset:17632
	ds_read_b64_tr_b16 v[226:227], v185 offset:22240
	ds_read_b64_tr_b16 v[228:229], v185 offset:26848
	ds_read_b64_tr_b16 v[230:231], v185 offset:31456
	s_add_i32 s64, s12, 2
	s_min_u32 s65, s64, 35
	s_sub_i32 s48, 3, s65
	s_sub_i32 s49, 39, s65
	s_cmp_lt_u32 s65, 4
	s_cselect_b32 s48, s48, s49
	s_cmp_eq_u32 s31, 0
	s_cselect_b32 s54, s65, s48
	s_lshl_b32 s48, s54, 6
	s_add_i32 s49, s33, s48
	s_add_i32 s48, s34, s48
	s_cmp_lt_u32 s54, 4
	s_cselect_b32 s55, s49, s48
	s_mul_i32 s0, s55, s30
	s_mul_i32 s1, s55, 0x1800
	s_add_i32 s5, s100, 2
	s_sub_i32 s6, s5, 3
	s_cmp_ge_u32 s5, 3
	s_cselect_b32 s5, s6, s5
	s_mul_i32 s14, s5, 0xb000
	s_lshl_b32 s4, s5, 9
	s_add_i32 s14, s14, s95
	s_add_u32 s56, s16, s0
	s_addc_u32 s57, s17, 0
	s_add_u32 s58, s18, s0
	s_addc_u32 s59, s19, 0
	s_add_u32 s60, s20, s1
	s_addc_u32 s61, s21, 0
	s_add_i32 s7, s14, 0
	s_mov_b32 m0, s7
	s_nop 0
	global_load_lds_dwordx4 v232, s[56:57]
	s_add_i32 s7, s14, 8192
	s_mov_b32 m0, s7
	s_nop 0
	global_load_lds_dwordx4 v233, s[56:57]
	s_cmp_eq_u32 s35, 0
	s_cselect_b64 s[2:3], s[56:57], s[58:59]
	s_add_i32 s7, s14, 16384
	s_mov_b32 m0, s7
	s_nop 0
	global_load_lds_dwordx4 v234, s[2:3]
	s_add_i32 s7, s14, 24576
	s_mov_b32 m0, s7
	s_nop 0
	global_load_lds_dwordx4 v235, s[58:59]
	s_cmp_lt_u32 s35, 3
	s_cselect_b64 s[2:3], s[58:59], s[60:61]
	s_add_i32 s7, s14, 32768
	s_mov_b32 m0, s7
	s_nop 0
	global_load_lds_dwordx4 v236, s[2:3]
	s_add_i32 s7, s14, 40960
	s_mov_b32 m0, s7
	s_nop 0
	global_load_lds_dwordx4 v237, s[60:61]
	s_waitcnt lgkmcnt(15)
	v_mfma_f32_16x16x32_bf16 v[2:5], v[62:65], v[126:129], v[2:5]
	v_mfma_f32_16x16x32_bf16 v[2:5], v[66:69], v[130:133], v[2:5]
	v_mfma_f32_16x16x32_bf16 v[6:9], v[70:73], v[126:129], v[6:9]
	v_mfma_f32_16x16x32_bf16 v[6:9], v[74:77], v[130:133], v[6:9]
	v_mfma_f32_16x16x32_bf16 v[10:13], v[78:81], v[126:129], v[10:13]
	v_mfma_f32_16x16x32_bf16 v[10:13], v[82:85], v[130:133], v[10:13]
	v_mfma_f32_16x16x32_bf16 v[14:17], v[86:89], v[126:129], v[14:17]
	v_mfma_f32_16x16x32_bf16 v[14:17], v[90:93], v[130:133], v[14:17]
	v_mfma_f32_16x16x32_bf16 v[34:37], v[150:153], v[94:97], 0
	v_mfma_f32_16x16x32_bf16 v[38:41], v[150:153], v[110:113], 0
	v_mfma_f32_16x16x32_bf16 v[34:37], v[154:157], v[98:101], v[34:37]
	v_mfma_f32_16x16x32_bf16 v[38:41], v[154:157], v[114:117], v[38:41]
	v_mfma_f32_16x16x32_bf16 v[34:37], v[158:161], v[102:105], v[34:37]
	v_mfma_f32_16x16x32_bf16 v[38:41], v[158:161], v[118:121], v[38:41]
	v_mfma_f32_16x16x32_bf16 v[34:37], v[162:165], v[106:109], v[34:37]
	v_mfma_f32_16x16x32_bf16 v[38:41], v[162:165], v[122:125], v[38:41]
	s_nop 7
	s_barrier
	s_cmp_gt_u32 s35, 1
	s_cbranch_scc1 .Lp8_nodec_11
	s_lshl_b32 s5, s54, 9
	s_add_u32 s2, s22, s5
	s_addc_u32 s3, s23, 0
	s_lshr_b32 s6, s95, 2
	s_add_i32 s6, s6, s4
	s_add_i32 s6, s6, 0x21000
	s_mov_b32 m0, s6
	s_nop 0
	global_load_lds_dword v194, s[2:3]
.Lp8_nodec_11:
	s_cmp_eq_u32 s36, 3
	s_cbranch_scc1 .Lp8_noa_12
	ds_read_b128 v[62:65], v56 offset:0
	ds_read_b128 v[66:69], v56 offset:64
	ds_read_b128 v[70:73], v56 offset:128
	ds_read_b128 v[74:77], v56 offset:192
	ds_read_b128 v[166:169], v54 offset:17408
	ds_read_b128 v[170:173], v54 offset:17472
	ds_read_b128 v[174:177], v54 offset:17536
	ds_read_b128 v[178:181], v54 offset:17600
	s_cmp_eq_u32 s98, s99
	s_cbranch_scc1 .Lp8_noa_12
	ds_read_b128 v[200:203], v55 offset:17408
	ds_read_b128 v[204:207], v55 offset:17472
	ds_read_b128 v[208:211], v55 offset:17536
	ds_read_b128 v[212:215], v55 offset:17600
.Lp8_noa_12:
	s_cmp_eq_u32 s36, 3
	s_cbranch_scc1 .Lp8_noat_13
	s_waitcnt lgkmcnt(0)
	v_mfma_f32_16x16x32_bf16 v[42:45], v[166:169], v[62:65], 0
	v_mfma_f32_16x16x32_bf16 v[42:45], v[170:173], v[66:69], v[42:45]
	v_mfma_f32_16x16x32_bf16 v[42:45], v[174:177], v[70:73], v[42:45]
	v_mfma_f32_16x16x32_bf16 v[42:45], v[178:181], v[74:77], v[42:45]
	s_cmp_eq_u32 s98, s99
	s_nop 6
	s_cbranch_scc1 .Lp8_nob1_13
	v_mfma_f32_16x16x32_bf16 v[46:49], v[200:203], v[62:65], 0
	v_mfma_f32_16x16x32_bf16 v[46:49], v[204:207], v[66:69], v[46:49]
	v_mfma_f32_16x16x32_bf16 v[46:49], v[208:211], v[70:73], v[46:49]
	v_mfma_f32_16x16x32_bf16 v[46:49], v[212:215], v[74:77], v[46:49]
	s_nop 7

.Lp8_noat_13:
	s_waitcnt lgkmcnt(0)
	s_barrier
	ds_read_b128 v[150:153], v59 offset:0
	ds_read_b128 v[154:157], v59 offset:7680
	ds_read_b128 v[158:161], v59 offset:7744
	ds_read_b128 v[166:169], v188 offset:0
	ds_read_b128 v[170:173], v188 offset:64
	ds_read_b128 v[174:177], v188 offset:128
	ds_read_b128 v[178:181], v188 offset:192
	ds_read_b128 v[200:203], v188 offset:256
	ds_read_b128 v[204:207], v188 offset:320
	ds_read_b128 v[208:211], v188 offset:384
	ds_read_b128 v[212:215], v188 offset:448
	v_mfma_f32_16x16x32_bf16 v[18:21], v[134:137], v[126:129], v[18:21]
	v_mfma_f32_16x16x32_bf16 v[18:21], v[138:141], v[130:133], v[18:21]
	v_mfma_f32_16x16x32_bf16 v[22:25], v[142:145], v[126:129], v[22:25]
	v_mfma_f32_16x16x32_bf16 v[22:25], v[146:149], v[130:133], v[22:25]
	v_mfma_f32_16x16x32_bf16 v[26:29], v[216:219], v[126:129], v[26:29]
	v_mfma_f32_16x16x32_bf16 v[26:29], v[220:223], v[130:133], v[26:29]
	v_mfma_f32_16x16x32_bf16 v[30:33], v[224:227], v[126:129], v[30:33]
	v_mfma_f32_16x16x32_bf16 v[30:33], v[228:231], v[130:133], v[30:33]
	s_waitcnt lgkmcnt(8)
	v_mfma_f32_16x16x32_bf16 v[34:37], v[126:129], v[150:153], v[34:37]
	v_mfma_f32_16x16x32_bf16 v[38:41], v[126:129], v[154:157], v[38:41]
	v_mfma_f32_16x16x32_bf16 v[38:41], v[130:133], v[158:161], v[38:41]
	s_waitcnt lgkmcnt(0)
	v_pk_mul_f32 v[2:3], v[2:3], v[166:167]
	v_pk_mul_f32 v[4:5], v[4:5], v[168:169]
	v_pk_mul_f32 v[6:7], v[6:7], v[170:171]
	v_pk_mul_f32 v[8:9], v[8:9], v[172:173]
	v_pk_mul_f32 v[10:11], v[10:11], v[174:175]
	v_pk_mul_f32 v[12:13], v[12:13], v[176:177]
	v_pk_mul_f32 v[14:15], v[14:15], v[178:179]
	v_pk_mul_f32 v[16:17], v[16:17], v[180:181]
	v_pk_mul_f32 v[18:19], v[18:19], v[200:201]
	v_pk_mul_f32 v[20:21], v[20:21], v[202:203]
	v_pk_mul_f32 v[22:23], v[22:23], v[204:205]
	v_pk_mul_f32 v[24:25], v[24:25], v[206:207]
	v_pk_mul_f32 v[26:27], v[26:27], v[208:209]
	v_pk_mul_f32 v[28:29], v[28:29], v[210:211]
	v_pk_mul_f32 v[30:31], v[30:31], v[212:213]
	v_pk_mul_f32 v[32:33], v[32:33], v[214:215]
	v_cvt_pk_bf16_f32 v50, v34, v35
	v_cvt_pk_bf16_f32 v51, v36, v37
	global_store_dwordx2 v247, v[50:51], s[8:9]
	v_cvt_pk_bf16_f32 v52, v38, v39
	v_cvt_pk_bf16_f32 v53, v40, v41
	global_store_dwordx2 v247, v[52:53], s[10:11]
	s_cmp_gt_u32 s12, 4
	s_cbranch_scc1 .Lp8_w10_14
	s_waitcnt vmcnt(6)
	s_branch .Lp8_wd_14

.Lp8_wd_14:
	s_barrier
	s_branch .Lp8_next
.Lp8_lat1:
	s_cmp_eq_u32 s12, 4
	s_cbranch_scc1 .Lp8_first_15
	ds_read_b128 v[150:153], v59 offset:2560
	ds_read_b128 v[154:157], v59 offset:5120
	ds_read_b128 v[158:161], v59 offset:5184
	v_mfma_f32_16x16x32_bf16 v[18:21], v[134:137], v[126:129], v[18:21]
	v_mfma_f32_16x16x32_bf16 v[18:21], v[138:141], v[130:133], v[18:21]
	v_mfma_f32_16x16x32_bf16 v[22:25], v[142:145], v[126:129], v[22:25]
	v_mfma_f32_16x16x32_bf16 v[22:25], v[146:149], v[130:133], v[22:25]
	v_mfma_f32_16x16x32_bf16 v[26:29], v[216:219], v[126:129], v[26:29]
	v_mfma_f32_16x16x32_bf16 v[26:29], v[220:223], v[130:133], v[26:29]
	v_mfma_f32_16x16x32_bf16 v[30:33], v[224:227], v[126:129], v[30:33]
	v_mfma_f32_16x16x32_bf16 v[30:33], v[228:231], v[130:133], v[30:33]
	s_waitcnt lgkmcnt(0)
	v_mfma_f32_16x16x32_bf16 v[34:37], v[126:129], v[150:153], v[34:37]
	v_mfma_f32_16x16x32_bf16 v[38:41], v[126:129], v[154:157], v[38:41]
	v_mfma_f32_16x16x32_bf16 v[38:41], v[130:133], v[158:161], v[38:41]
	v_pk_mul_f32 v[2:3], v[2:3], v[166:167]
	v_pk_mul_f32 v[4:5], v[4:5], v[168:169]
	v_pk_mul_f32 v[6:7], v[6:7], v[170:171]
	v_pk_mul_f32 v[8:9], v[8:9], v[172:173]
	v_pk_mul_f32 v[10:11], v[10:11], v[174:175]
	v_pk_mul_f32 v[12:13], v[12:13], v[176:177]
	v_pk_mul_f32 v[14:15], v[14:15], v[178:179]
	v_pk_mul_f32 v[16:17], v[16:17], v[180:181]
	v_pk_mul_f32 v[18:19], v[18:19], v[200:201]
	v_pk_mul_f32 v[20:21], v[20:21], v[202:203]
	v_pk_mul_f32 v[22:23], v[22:23], v[204:205]
	v_pk_mul_f32 v[24:25], v[24:25], v[206:207]
	v_pk_mul_f32 v[26:27], v[26:27], v[208:209]
	v_pk_mul_f32 v[28:29], v[28:29], v[210:211]
	v_pk_mul_f32 v[30:31], v[30:31], v[212:213]
	v_pk_mul_f32 v[32:33], v[32:33], v[214:215]
	v_cvt_pk_bf16_f32 v50, v34, v35
	v_cvt_pk_bf16_f32 v51, v36, v37
	global_store_dwordx2 v247, v[50:51], s[76:77]
	v_cvt_pk_bf16_f32 v52, v38, v39
	v_cvt_pk_bf16_f32 v53, v40, v41
	global_store_dwordx2 v247, v[52:53], s[78:79]
	s_nop 0
.Lp8_first_15:
	s_sub_i32 s48, 3, s12
	s_sub_i32 s49, 39, s12
	s_cmp_lt_u32 s12, 4
	s_cselect_b32 s48, s48, s49
	s_cmp_eq_u32 s31, 0
	s_cselect_b32 s54, s12, s48
	s_lshl_b32 s48, s54, 6
	s_add_i32 s49, s33, s48
	s_add_i32 s48, s34, s48
	s_cmp_lt_u32 s54, 4
	s_cselect_b32 s55, s49, s48
	s_add_i32 s48, s55, 16
	s_add_i32 s49, s55, 32
	s_cmp_eq_u32 s31, 0
	s_cselect_b32 s48, s48, s49
	s_lshl_b32 s48, s48, 11
	s_add_u32 s8, s28, s48
	s_addc_u32 s9, s29, 0
	s_add_i32 s48, s55, 32
	s_add_i32 s49, s55, 16
	s_cmp_eq_u32 s31, 0
	s_cselect_b32 s48, s48, s49
	s_lshl_b32 s48, s48, 11
	s_add_u32 s10, s28, s48
	s_addc_u32 s11, s29, 0
	v_cvt_pk_bf16_f32 v150, v2, v3
	v_cvt_pk_bf16_f32 v151, v4, v5
	v_cvt_pk_bf16_f32 v152, v6, v7
	v_cvt_pk_bf16_f32 v153, v8, v9
	v_cvt_pk_bf16_f32 v154, v10, v11
	v_cvt_pk_bf16_f32 v155, v12, v13
	v_cvt_pk_bf16_f32 v156, v14, v15
	v_cvt_pk_bf16_f32 v157, v16, v17
	v_cvt_pk_bf16_f32 v158, v18, v19
	v_cvt_pk_bf16_f32 v159, v20, v21
	v_cvt_pk_bf16_f32 v160, v22, v23
	v_cvt_pk_bf16_f32 v161, v24, v25
	v_cvt_pk_bf16_f32 v162, v26, v27
	v_cvt_pk_bf16_f32 v163, v28, v29
	v_cvt_pk_bf16_f32 v164, v30, v31
	v_cvt_pk_bf16_f32 v165, v32, v33
	ds_read_b64_tr_b16 v[126:127], v184 offset:35840
	ds_read_b64_tr_b16 v[128:129], v184 offset:38144
	ds_read_b64_tr_b16 v[130:131], v184 offset:40448
	ds_read_b64_tr_b16 v[132:133], v184 offset:42752
	ds_read_b64_tr_b16 v[62:63], v185 offset:17408
	ds_read_b64_tr_b16 v[64:65], v185 offset:22016
	ds_read_b64_tr_b16 v[66:67], v185 offset:26624
	ds_read_b64_tr_b16 v[68:69], v185 offset:31232
	ds_read_b64_tr_b16 v[70:71], v185 offset:17440
	ds_read_b64_tr_b16 v[72:73], v185 offset:22048
	ds_read_b64_tr_b16 v[74:75], v185 offset:26656
	ds_read_b64_tr_b16 v[76:77], v185 offset:31264
	ds_read_b64_tr_b16 v[78:79], v185 offset:17472
	ds_read_b64_tr_b16 v[80:81], v185 offset:22080
	ds_read_b64_tr_b16 v[82:83], v185 offset:26688
	ds_read_b64_tr_b16 v[84:85], v185 offset:31296
	ds_read_b64_tr_b16 v[86:87], v185 offset:17504
	ds_read_b64_tr_b16 v[88:89], v185 offset:22112
	ds_read_b64_tr_b16 v[90:91], v185 offset:26720
	ds_read_b64_tr_b16 v[92:93], v185 offset:31328
	ds_read_b64 v[94:95], v183 offset:4352
	ds_read_b64 v[96:97], v183 offset:4384
	ds_read_b64 v[98:99], v183 offset:4416
	ds_read_b64 v[100:101], v183 offset:4448
	ds_read_b64 v[102:103], v183 offset:4480
	ds_read_b64 v[104:105], v183 offset:4512
	ds_read_b64 v[106:107], v183 offset:4544
	ds_read_b64 v[108:109], v183 offset:4576
	ds_read_b64 v[110:111], v183 offset:8704
	ds_read_b64 v[112:113], v183 offset:8736
	ds_read_b64 v[114:115], v183 offset:8768
	ds_read_b64 v[116:117], v183 offset:8800
	ds_read_b64 v[118:119], v183 offset:8832
	ds_read_b64 v[120:121], v183 offset:8864
	ds_read_b64 v[122:123], v183 offset:8896
	ds_read_b64 v[124:125], v183 offset:8928
	ds_read_b64_tr_b16 v[134:135], v185 offset:17536
	ds_read_b64_tr_b16 v[136:137], v185 offset:22144
	ds_read_b64_tr_b16 v[138:139], v185 offset:26752
	ds_read_b64_tr_b16 v[140:141], v185 offset:31360
	ds_read_b64_tr_b16 v[142:143], v185 offset:17568
	ds_read_b64_tr_b16 v[144:145], v185 offset:22176
	ds_read_b64_tr_b16 v[146:147], v185 offset:26784
	ds_read_b64_tr_b16 v[148:149], v185 offset:31392
	ds_read_b64_tr_b16 v[216:217], v185 offset:17600
	ds_read_b64_tr_b16 v[218:219], v185 offset:22208
	ds_read_b64_tr_b16 v[220:221], v185 offset:26816
	ds_read_b64_tr_b16 v[222:223], v185 offset:31424
	ds_read_b64_tr_b16 v[224:225], v185 offset:17632
	ds_read_b64_tr_b16 v[226:227], v185 offset:22240
	ds_read_b64_tr_b16 v[228:229], v185 offset:26848
	ds_read_b64_tr_b16 v[230:231], v185 offset:31456
	s_add_i32 s64, s12, 2
	s_min_u32 s65, s64, 35
	s_sub_i32 s48, 3, s65
	s_sub_i32 s49, 39, s65
	s_cmp_lt_u32 s65, 4
	s_cselect_b32 s48, s48, s49
	s_cmp_eq_u32 s31, 0
	s_cselect_b32 s54, s65, s48
	s_lshl_b32 s48, s54, 6
	s_add_i32 s49, s33, s48
	s_add_i32 s48, s34, s48
	s_cmp_lt_u32 s54, 4
	s_cselect_b32 s55, s49, s48
	s_mul_i32 s0, s55, s30
	s_mul_i32 s1, s55, 0x1800
	s_add_i32 s5, s100, 2
	s_sub_i32 s6, s5, 3
	s_cmp_ge_u32 s5, 3
	s_cselect_b32 s5, s6, s5
	s_mul_i32 s14, s5, 0xb000
	s_lshl_b32 s4, s5, 9
	s_add_i32 s14, s14, s95
	s_add_u32 s56, s16, s0
	s_addc_u32 s57, s17, 0
	s_add_u32 s58, s18, s0
	s_addc_u32 s59, s19, 0
	s_add_u32 s60, s20, s1
	s_addc_u32 s61, s21, 0
	s_add_i32 s7, s14, 0
	s_mov_b32 m0, s7
	s_nop 0
	global_load_lds_dwordx4 v232, s[56:57]
	s_add_i32 s7, s14, 8192
	s_mov_b32 m0, s7
	s_nop 0
	global_load_lds_dwordx4 v233, s[56:57]
	s_cmp_eq_u32 s35, 0
	s_cselect_b64 s[2:3], s[56:57], s[58:59]
	s_add_i32 s7, s14, 16384
	s_mov_b32 m0, s7
	s_nop 0
	global_load_lds_dwordx4 v234, s[2:3]
	s_add_i32 s7, s14, 24576
	s_mov_b32 m0, s7
	s_nop 0
	global_load_lds_dwordx4 v235, s[58:59]
	s_cmp_lt_u32 s35, 3
	s_cselect_b64 s[2:3], s[58:59], s[60:61]
	s_add_i32 s7, s14, 32768
	s_mov_b32 m0, s7
	s_nop 0
	global_load_lds_dwordx4 v236, s[2:3]
	s_barrier
	s_waitcnt lgkmcnt(15)
	v_mfma_f32_16x16x32_bf16 v[2:5], v[62:65], v[126:129], v[2:5]
	v_mfma_f32_16x16x32_bf16 v[2:5], v[66:69], v[130:133], v[2:5]
	v_mfma_f32_16x16x32_bf16 v[6:9], v[70:73], v[126:129], v[6:9]
	v_mfma_f32_16x16x32_bf16 v[6:9], v[74:77], v[130:133], v[6:9]
	v_mfma_f32_16x16x32_bf16 v[10:13], v[78:81], v[126:129], v[10:13]
	v_mfma_f32_16x16x32_bf16 v[10:13], v[82:85], v[130:133], v[10:13]
	v_mfma_f32_16x16x32_bf16 v[14:17], v[86:89], v[126:129], v[14:17]
	v_mfma_f32_16x16x32_bf16 v[14:17], v[90:93], v[130:133], v[14:17]
	v_mfma_f32_16x16x32_bf16 v[34:37], v[150:153], v[94:97], 0
	v_mfma_f32_16x16x32_bf16 v[38:41], v[150:153], v[110:113], 0
	v_mfma_f32_16x16x32_bf16 v[34:37], v[154:157], v[98:101], v[34:37]
	v_mfma_f32_16x16x32_bf16 v[38:41], v[154:157], v[114:117], v[38:41]
	v_mfma_f32_16x16x32_bf16 v[34:37], v[158:161], v[102:105], v[34:37]
	v_mfma_f32_16x16x32_bf16 v[38:41], v[158:161], v[118:121], v[38:41]
	v_mfma_f32_16x16x32_bf16 v[34:37], v[162:165], v[106:109], v[34:37]
	v_mfma_f32_16x16x32_bf16 v[38:41], v[162:165], v[122:125], v[38:41]
	s_waitcnt lgkmcnt(0)
	s_cmp_eq_u32 s36, 3
	s_nop 5
	s_cbranch_scc1 .Lp8_noa_17
	ds_read_b128 v[62:65], v56 offset:0
	ds_read_b128 v[66:69], v56 offset:64
	ds_read_b128 v[70:73], v56 offset:128
	ds_read_b128 v[74:77], v56 offset:192
	ds_read_b128 v[166:169], v54 offset:17408
	ds_read_b128 v[170:173], v54 offset:17472
	ds_read_b128 v[174:177], v54 offset:17536
	ds_read_b128 v[178:181], v54 offset:17600
	s_cmp_eq_u32 s98, s99
	s_cbranch_scc1 .Lp8_noa_17
	ds_read_b128 v[200:203], v55 offset:17408
	ds_read_b128 v[204:207], v55 offset:17472
	ds_read_b128 v[208:211], v55 offset:17536
	ds_read_b128 v[212:215], v55 offset:17600
.Lp8_noa_17:
	s_barrier
	s_cmp_eq_u32 s36, 3
	s_cbranch_scc1 .Lp8_noat_18
	s_waitcnt lgkmcnt(0)
	v_mfma_f32_16x16x32_bf16 v[42:45], v[166:169], v[62:65], 0
	v_mfma_f32_16x16x32_bf16 v[42:45], v[170:173], v[66:69], v[42:45]
	v_mfma_f32_16x16x32_bf16 v[42:45], v[174:177], v[70:73], v[42:45]
	v_mfma_f32_16x16x32_bf16 v[42:45], v[178:181], v[74:77], v[42:45]
	s_cmp_eq_u32 s98, s99
	s_nop 6
	s_cbranch_scc1 .Lp8_nob1_18
	v_mfma_f32_16x16x32_bf16 v[46:49], v[200:203], v[62:65], 0
	v_mfma_f32_16x16x32_bf16 v[46:49], v[204:207], v[66:69], v[46:49]
	v_mfma_f32_16x16x32_bf16 v[46:49], v[208:211], v[70:73], v[46:49]
	v_mfma_f32_16x16x32_bf16 v[46:49], v[212:215], v[74:77], v[46:49]
	s_nop 7

.Lp8_noat_18:
	ds_read_b128 v[166:169], v188 offset:0
	ds_read_b128 v[170:173], v188 offset:64
	ds_read_b128 v[174:177], v188 offset:128
	ds_read_b128 v[178:181], v188 offset:192
	ds_read_b128 v[200:203], v188 offset:256
	ds_read_b128 v[204:207], v188 offset:320
	ds_read_b128 v[208:211], v188 offset:384
	ds_read_b128 v[212:215], v188 offset:448
	s_mov_b64 s[76:77], s[8:9]
	s_mov_b64 s[78:79], s[10:11]
	s_waitcnt vmcnt(5)
	s_waitcnt lgkmcnt(8)
	s_barrier
.Lp8_next:
	s_add_i32 s12, s12, 1
	s_add_i32 s100, s100, 1
	s_cmp_eq_u32 s100, 3
	s_cselect_b32 s100, 0, s100
	s_cmp_lt_u32 s12, 36
	s_cbranch_scc1 .Lp8_step
	s_cmp_eq_u32 s37, 0
	s_cbranch_scc1 .Lp8_done
	ds_read_b128 v[150:153], v59 offset:2560
	ds_read_b128 v[154:157], v59 offset:5120
	ds_read_b128 v[158:161], v59 offset:5184
	v_mfma_f32_16x16x32_bf16 v[18:21], v[134:137], v[126:129], v[18:21]
	v_mfma_f32_16x16x32_bf16 v[18:21], v[138:141], v[130:133], v[18:21]
	v_mfma_f32_16x16x32_bf16 v[22:25], v[142:145], v[126:129], v[22:25]
	v_mfma_f32_16x16x32_bf16 v[22:25], v[146:149], v[130:133], v[22:25]
	v_mfma_f32_16x16x32_bf16 v[26:29], v[216:219], v[126:129], v[26:29]
	v_mfma_f32_16x16x32_bf16 v[26:29], v[220:223], v[130:133], v[26:29]
	v_mfma_f32_16x16x32_bf16 v[30:33], v[224:227], v[126:129], v[30:33]
	v_mfma_f32_16x16x32_bf16 v[30:33], v[228:231], v[130:133], v[30:33]
	s_waitcnt lgkmcnt(0)
	v_mfma_f32_16x16x32_bf16 v[34:37], v[126:129], v[150:153], v[34:37]
	v_mfma_f32_16x16x32_bf16 v[38:41], v[126:129], v[154:157], v[38:41]
	v_mfma_f32_16x16x32_bf16 v[38:41], v[130:133], v[158:161], v[38:41]
	v_pk_mul_f32 v[2:3], v[2:3], v[166:167]
	v_pk_mul_f32 v[4:5], v[4:5], v[168:169]
	v_pk_mul_f32 v[6:7], v[6:7], v[170:171]
	v_pk_mul_f32 v[8:9], v[8:9], v[172:173]
	v_pk_mul_f32 v[10:11], v[10:11], v[174:175]
	v_pk_mul_f32 v[12:13], v[12:13], v[176:177]
	v_pk_mul_f32 v[14:15], v[14:15], v[178:179]
	v_pk_mul_f32 v[16:17], v[16:17], v[180:181]
	v_pk_mul_f32 v[18:19], v[18:19], v[200:201]
	v_pk_mul_f32 v[20:21], v[20:21], v[202:203]
	v_pk_mul_f32 v[22:23], v[22:23], v[204:205]
	v_pk_mul_f32 v[24:25], v[24:25], v[206:207]
	v_pk_mul_f32 v[26:27], v[26:27], v[208:209]
	v_pk_mul_f32 v[28:29], v[28:29], v[210:211]
	v_pk_mul_f32 v[30:31], v[30:31], v[212:213]
	v_pk_mul_f32 v[32:33], v[32:33], v[214:215]
	v_cvt_pk_bf16_f32 v50, v34, v35
	v_cvt_pk_bf16_f32 v51, v36, v37
	global_store_dwordx2 v247, v[50:51], s[76:77]
	v_cvt_pk_bf16_f32 v52, v38, v39
	v_cvt_pk_bf16_f32 v53, v40, v41
	global_store_dwordx2 v247, v[52:53], s[78:79]
	s_nop 0
